# q/k RMS-norm + rope block: q and k in one pass, DPP row reductions instead of ds_bpermute ladders
# baseline (speedup 1.0000x reference)
; #define PRM (*KP())
; DI void phase_post(LAS unsigned char* lds, int l, bool do_qk) {
;     ...
;     if (do_qk) {
;         const int lp = lane & 31, d0 = 2 * lp, dd = d0 & 31, i0 = dd & 15; const bool axis = d0 >= 32; const float sgn = dd < 16 ? -1.f : 1.f;
;         const float inv0 = exp2f(-(float)i0 * (13.287712379549449f / 16.f)), inv1 = exp2f(-(float)(i0 + 1) * (13.287712379549449f / 16.f));
;         const float gq0 = PRM.in[I_QG][(size_t)l * 64 + d0], gq1 = PRM.in[I_QG][(size_t)l * 64 + d0 + 1], gk0 = PRM.in[I_KG][(size_t)l * 64 + d0], gk1 = PRM.in[I_KG][(size_t)l * 64 + d0 + 1];
;         for (int row = bx * 8 + wid; row < MROWS; row += G * 8) {
;             const int t = row % TPB; const bool isctx = t < CTXL; const int tl = t - CTXL;
;             const float pos = (float)(axis ? (tl & 63) : (tl >> 6));
;             float s0 = 0.f, c0 = 1.f, s1 = 0.f, c1 = 1.f;
;             if (!isctx) { const float a0 = pos * inv0, a1 = pos * inv1; s0 = __sinf(a0); c0 = __cosf(a0); s1 = __sinf(a1); c1 = __cosf(a1); }
;             for (int which = 0; which < 2; ++which) {
;                 bf16_t* base = (bf16_t*)(ws + (which ? WS_KB : WS_QB)) + (size_t)row * 1024;
;                 const float g0 = which ? gk0 : gq0, g1 = which ? gk1 : gq1;
;                 unsigned wv[8];
; #pragma unroll
;                 for (int it = 0; it < 8; ++it) wv[it] = *(const unsigned*)(base + it * 128 + lane * 2);
; #pragma unroll
;                 for (int it = 0; it < 8; ++it) { const unsigned w = wv[it];
;                     const float x0 = bf2f(w & 0xffff), x1 = bf2f(w >> 16); float ss = x0 * x0 + x1 * x1;
; #pragma unroll
;                     for (int s = 1; s < 32; s <<= 1) ss += __shfl_xor(ss, s);
;                     const float rs = rsqrtf(ss * (1.f / 64.f) + EPS); float y0 = x0 * rs * g0, y1 = x1 * rs * g1;
.LBB0_326:
	s_mov_b32 s40, 0xa488000
	v_lshl_add_u64 v[6:7], v[4:5], 0, s[40:41]
	s_mov_b32 s40, 0xc588000
	v_lshl_add_u64 v[8:9], v[4:5], 0, s[40:41]
	global_load_dword v46, v[6:7], off
	global_load_dword v47, v[6:7], off offset:256
	global_load_dword v48, v[6:7], off offset:512
	global_load_dword v49, v[6:7], off offset:768
	global_load_dword v50, v[6:7], off offset:1024
	global_load_dword v51, v[6:7], off offset:1280
	global_load_dword v52, v[6:7], off offset:1536
	global_load_dword v53, v[6:7], off offset:1792
	global_load_dword v54, v[8:9], off
	global_load_dword v55, v[8:9], off offset:256
	global_load_dword v56, v[8:9], off offset:512
	global_load_dword v57, v[8:9], off offset:768
	global_load_dword v58, v[8:9], off offset:1024
	global_load_dword v59, v[8:9], off offset:1280
	global_load_dword v60, v[8:9], off offset:1536
	global_load_dword v61, v[8:9], off offset:1792
	v_mov_b32_e32 v174, 0x358637bd
	s_waitcnt vmcnt(15)
	v_lshlrev_b32_e32 v62, 16, v46
	v_and_b32_e32 v78, 0xffff0000, v46
	v_mul_f32_e32 v94, v62, v62
	s_waitcnt vmcnt(14)
	v_lshlrev_b32_e32 v63, 16, v47
	v_and_b32_e32 v79, 0xffff0000, v47
	v_mul_f32_e32 v95, v63, v63
	s_waitcnt vmcnt(13)
	v_lshlrev_b32_e32 v64, 16, v48
	v_and_b32_e32 v80, 0xffff0000, v48
	v_mul_f32_e32 v96, v64, v64
	s_waitcnt vmcnt(12)
	v_lshlrev_b32_e32 v65, 16, v49
	v_and_b32_e32 v81, 0xffff0000, v49
	v_mul_f32_e32 v97, v65, v65
	s_waitcnt vmcnt(11)
	v_lshlrev_b32_e32 v66, 16, v50
	v_and_b32_e32 v82, 0xffff0000, v50
	v_mul_f32_e32 v98, v66, v66
	s_waitcnt vmcnt(10)
	v_lshlrev_b32_e32 v67, 16, v51
	v_and_b32_e32 v83, 0xffff0000, v51
	v_mul_f32_e32 v99, v67, v67
	s_waitcnt vmcnt(9)
	v_lshlrev_b32_e32 v68, 16, v52
	v_and_b32_e32 v84, 0xffff0000, v52
	v_mul_f32_e32 v100, v68, v68
	s_waitcnt vmcnt(8)
	v_lshlrev_b32_e32 v69, 16, v53
	v_and_b32_e32 v85, 0xffff0000, v53
	v_mul_f32_e32 v101, v69, v69
	s_waitcnt vmcnt(7)
	v_lshlrev_b32_e32 v70, 16, v54
	v_and_b32_e32 v86, 0xffff0000, v54
	v_mul_f32_e32 v102, v70, v70
	s_waitcnt vmcnt(6)
	v_lshlrev_b32_e32 v71, 16, v55
	v_and_b32_e32 v87, 0xffff0000, v55
	v_mul_f32_e32 v103, v71, v71
	s_waitcnt vmcnt(5)
	v_lshlrev_b32_e32 v72, 16, v56
	v_and_b32_e32 v88, 0xffff0000, v56
	v_mul_f32_e32 v104, v72, v72
	s_waitcnt vmcnt(4)
	v_lshlrev_b32_e32 v73, 16, v57
	v_and_b32_e32 v89, 0xffff0000, v57
	v_mul_f32_e32 v105, v73, v73
	s_waitcnt vmcnt(3)
	v_lshlrev_b32_e32 v74, 16, v58
	v_and_b32_e32 v90, 0xffff0000, v58
	v_mul_f32_e32 v106, v74, v74
	s_waitcnt vmcnt(2)
	v_lshlrev_b32_e32 v75, 16, v59
	v_and_b32_e32 v91, 0xffff0000, v59
	v_mul_f32_e32 v107, v75, v75
	s_waitcnt vmcnt(1)
	v_lshlrev_b32_e32 v76, 16, v60
	v_and_b32_e32 v92, 0xffff0000, v60
	v_mul_f32_e32 v108, v76, v76
	s_waitcnt vmcnt(0)
	v_lshlrev_b32_e32 v77, 16, v61
	v_and_b32_e32 v93, 0xffff0000, v61
	v_mul_f32_e32 v109, v77, v77
	v_fmac_f32_e32 v94, v78, v78
	v_fmac_f32_e32 v95, v79, v79
	v_fmac_f32_e32 v96, v80, v80
	v_fmac_f32_e32 v97, v81, v81
	v_fmac_f32_e32 v98, v82, v82
	v_fmac_f32_e32 v99, v83, v83
	v_fmac_f32_e32 v100, v84, v84
	v_fmac_f32_e32 v101, v85, v85
	v_fmac_f32_e32 v102, v86, v86
	v_fmac_f32_e32 v103, v87, v87
	v_fmac_f32_e32 v104, v88, v88
	v_fmac_f32_e32 v105, v89, v89
	v_fmac_f32_e32 v106, v90, v90
	v_fmac_f32_e32 v107, v91, v91
	v_fmac_f32_e32 v108, v92, v92
	v_fmac_f32_e32 v109, v93, v93
	v_add_f32_dpp v94, v94, v94 quad_perm:[1,0,3,2] row_mask:0xf bank_mask:0xf
	v_add_f32_dpp v95, v95, v95 quad_perm:[1,0,3,2] row_mask:0xf bank_mask:0xf
	v_add_f32_dpp v96, v96, v96 quad_perm:[1,0,3,2] row_mask:0xf bank_mask:0xf
	v_add_f32_dpp v97, v97, v97 quad_perm:[1,0,3,2] row_mask:0xf bank_mask:0xf
	v_add_f32_dpp v98, v98, v98 quad_perm:[1,0,3,2] row_mask:0xf bank_mask:0xf
	v_add_f32_dpp v99, v99, v99 quad_perm:[1,0,3,2] row_mask:0xf bank_mask:0xf
	v_add_f32_dpp v100, v100, v100 quad_perm:[1,0,3,2] row_mask:0xf bank_mask:0xf
	v_add_f32_dpp v101, v101, v101 quad_perm:[1,0,3,2] row_mask:0xf bank_mask:0xf
	v_add_f32_dpp v102, v102, v102 quad_perm:[1,0,3,2] row_mask:0xf bank_mask:0xf
	v_add_f32_dpp v103, v103, v103 quad_perm:[1,0,3,2] row_mask:0xf bank_mask:0xf
	v_add_f32_dpp v104, v104, v104 quad_perm:[1,0,3,2] row_mask:0xf bank_mask:0xf
	v_add_f32_dpp v105, v105, v105 quad_perm:[1,0,3,2] row_mask:0xf bank_mask:0xf
	v_add_f32_dpp v106, v106, v106 quad_perm:[1,0,3,2] row_mask:0xf bank_mask:0xf
	v_add_f32_dpp v107, v107, v107 quad_perm:[1,0,3,2] row_mask:0xf bank_mask:0xf
	v_add_f32_dpp v108, v108, v108 quad_perm:[1,0,3,2] row_mask:0xf bank_mask:0xf
	v_add_f32_dpp v109, v109, v109 quad_perm:[1,0,3,2] row_mask:0xf bank_mask:0xf
	v_add_f32_dpp v94, v94, v94 quad_perm:[2,3,0,1] row_mask:0xf bank_mask:0xf
	v_add_f32_dpp v95, v95, v95 quad_perm:[2,3,0,1] row_mask:0xf bank_mask:0xf
	v_add_f32_dpp v96, v96, v96 quad_perm:[2,3,0,1] row_mask:0xf bank_mask:0xf
	v_add_f32_dpp v97, v97, v97 quad_perm:[2,3,0,1] row_mask:0xf bank_mask:0xf
	v_add_f32_dpp v98, v98, v98 quad_perm:[2,3,0,1] row_mask:0xf bank_mask:0xf
	v_add_f32_dpp v99, v99, v99 quad_perm:[2,3,0,1] row_mask:0xf bank_mask:0xf
	v_add_f32_dpp v100, v100, v100 quad_perm:[2,3,0,1] row_mask:0xf bank_mask:0xf
	v_add_f32_dpp v101, v101, v101 quad_perm:[2,3,0,1] row_mask:0xf bank_mask:0xf
	v_add_f32_dpp v102, v102, v102 quad_perm:[2,3,0,1] row_mask:0xf bank_mask:0xf
	v_add_f32_dpp v103, v103, v103 quad_perm:[2,3,0,1] row_mask:0xf bank_mask:0xf
	v_add_f32_dpp v104, v104, v104 quad_perm:[2,3,0,1] row_mask:0xf bank_mask:0xf
	v_add_f32_dpp v105, v105, v105 quad_perm:[2,3,0,1] row_mask:0xf bank_mask:0xf
	v_add_f32_dpp v106, v106, v106 quad_perm:[2,3,0,1] row_mask:0xf bank_mask:0xf
	v_add_f32_dpp v107, v107, v107 quad_perm:[2,3,0,1] row_mask:0xf bank_mask:0xf
; DI void phase_post(LAS unsigned char* lds, int l, bool do_qk) {
;     ...
;                 for (int it = 0; it < 8; ++it) { const unsigned w = wv[it];
;                     const float x0 = bf2f(w & 0xffff), x1 = bf2f(w >> 16); float ss = x0 * x0 + x1 * x1;
; #pragma unroll
;                     for (int s = 1; s < 32; s <<= 1) ss += __shfl_xor(ss, s);
;                     const float rs = rsqrtf(ss * (1.f / 64.f) + EPS); float y0 = x0 * rs * g0, y1 = x1 * rs * g1;
;                     const float p0 = __shfl_xor(y0, 8), p1 = __shfl_xor(y1, 8);
	v_add_f32_dpp v108, v108, v108 quad_perm:[2,3,0,1] row_mask:0xf bank_mask:0xf
	v_add_f32_dpp v109, v109, v109 quad_perm:[2,3,0,1] row_mask:0xf bank_mask:0xf
	v_add_f32_dpp v94, v94, v94 row_ror:4 row_mask:0xf bank_mask:0xf
	v_add_f32_dpp v95, v95, v95 row_ror:4 row_mask:0xf bank_mask:0xf
	v_add_f32_dpp v96, v96, v96 row_ror:4 row_mask:0xf bank_mask:0xf
	v_add_f32_dpp v97, v97, v97 row_ror:4 row_mask:0xf bank_mask:0xf
	v_add_f32_dpp v98, v98, v98 row_ror:4 row_mask:0xf bank_mask:0xf
	v_add_f32_dpp v99, v99, v99 row_ror:4 row_mask:0xf bank_mask:0xf
	v_add_f32_dpp v100, v100, v100 row_ror:4 row_mask:0xf bank_mask:0xf
	v_add_f32_dpp v101, v101, v101 row_ror:4 row_mask:0xf bank_mask:0xf
	v_add_f32_dpp v102, v102, v102 row_ror:4 row_mask:0xf bank_mask:0xf
	v_add_f32_dpp v103, v103, v103 row_ror:4 row_mask:0xf bank_mask:0xf
	v_add_f32_dpp v104, v104, v104 row_ror:4 row_mask:0xf bank_mask:0xf
	v_add_f32_dpp v105, v105, v105 row_ror:4 row_mask:0xf bank_mask:0xf
	v_add_f32_dpp v106, v106, v106 row_ror:4 row_mask:0xf bank_mask:0xf
	v_add_f32_dpp v107, v107, v107 row_ror:4 row_mask:0xf bank_mask:0xf
	v_add_f32_dpp v108, v108, v108 row_ror:4 row_mask:0xf bank_mask:0xf
	v_add_f32_dpp v109, v109, v109 row_ror:4 row_mask:0xf bank_mask:0xf
	v_add_f32_dpp v94, v94, v94 row_ror:8 row_mask:0xf bank_mask:0xf
	v_add_f32_dpp v95, v95, v95 row_ror:8 row_mask:0xf bank_mask:0xf
	v_add_f32_dpp v96, v96, v96 row_ror:8 row_mask:0xf bank_mask:0xf
	v_add_f32_dpp v97, v97, v97 row_ror:8 row_mask:0xf bank_mask:0xf
	v_add_f32_dpp v98, v98, v98 row_ror:8 row_mask:0xf bank_mask:0xf
	v_add_f32_dpp v99, v99, v99 row_ror:8 row_mask:0xf bank_mask:0xf
	v_add_f32_dpp v100, v100, v100 row_ror:8 row_mask:0xf bank_mask:0xf
	v_add_f32_dpp v101, v101, v101 row_ror:8 row_mask:0xf bank_mask:0xf
	v_add_f32_dpp v102, v102, v102 row_ror:8 row_mask:0xf bank_mask:0xf
	v_add_f32_dpp v103, v103, v103 row_ror:8 row_mask:0xf bank_mask:0xf
	v_add_f32_dpp v104, v104, v104 row_ror:8 row_mask:0xf bank_mask:0xf
	v_add_f32_dpp v105, v105, v105 row_ror:8 row_mask:0xf bank_mask:0xf
	v_add_f32_dpp v106, v106, v106 row_ror:8 row_mask:0xf bank_mask:0xf
	v_add_f32_dpp v107, v107, v107 row_ror:8 row_mask:0xf bank_mask:0xf
	v_add_f32_dpp v108, v108, v108 row_ror:8 row_mask:0xf bank_mask:0xf
	v_add_f32_dpp v109, v109, v109 row_ror:8 row_mask:0xf bank_mask:0xf
	ds_bpermute_b32 v110, v22, v94
	ds_bpermute_b32 v111, v22, v95
	ds_bpermute_b32 v112, v22, v96
	ds_bpermute_b32 v113, v22, v97
	ds_bpermute_b32 v114, v22, v98
	ds_bpermute_b32 v115, v22, v99
	ds_bpermute_b32 v116, v22, v100
	ds_bpermute_b32 v117, v22, v101
	ds_bpermute_b32 v118, v22, v102
	ds_bpermute_b32 v119, v22, v103
	ds_bpermute_b32 v120, v22, v104
	ds_bpermute_b32 v121, v22, v105
	ds_bpermute_b32 v122, v22, v106
	ds_bpermute_b32 v123, v22, v107
	ds_bpermute_b32 v124, v22, v108
	ds_bpermute_b32 v125, v22, v109
	s_waitcnt lgkmcnt(15)
	v_add_f32_e32 v94, v94, v110
	s_waitcnt lgkmcnt(14)
	v_add_f32_e32 v95, v95, v111
	s_waitcnt lgkmcnt(13)
	v_add_f32_e32 v96, v96, v112
	s_waitcnt lgkmcnt(12)
	v_add_f32_e32 v97, v97, v113
	s_waitcnt lgkmcnt(11)
	v_add_f32_e32 v98, v98, v114
	s_waitcnt lgkmcnt(10)
	v_add_f32_e32 v99, v99, v115
	s_waitcnt lgkmcnt(9)
	v_add_f32_e32 v100, v100, v116
	s_waitcnt lgkmcnt(8)
	v_add_f32_e32 v101, v101, v117
	s_waitcnt lgkmcnt(7)
	v_add_f32_e32 v102, v102, v118
	s_waitcnt lgkmcnt(6)
	v_add_f32_e32 v103, v103, v119
	s_waitcnt lgkmcnt(5)
	v_add_f32_e32 v104, v104, v120
	s_waitcnt lgkmcnt(4)
	v_add_f32_e32 v105, v105, v121
	s_waitcnt lgkmcnt(3)
	v_add_f32_e32 v106, v106, v122
	s_waitcnt lgkmcnt(2)
	v_add_f32_e32 v107, v107, v123
	s_waitcnt lgkmcnt(1)
	v_add_f32_e32 v108, v108, v124
	s_waitcnt lgkmcnt(0)
	v_add_f32_e32 v109, v109, v125
	v_fma_f32 v94, v94, s58, v174
	v_fma_f32 v95, v95, s58, v174
	v_fma_f32 v96, v96, s58, v174
	v_fma_f32 v97, v97, s58, v174
	v_fma_f32 v98, v98, s58, v174
	v_fma_f32 v99, v99, s58, v174
	v_fma_f32 v100, v100, s58, v174
	v_fma_f32 v101, v101, s58, v174
	v_fma_f32 v102, v102, s58, v174
	v_fma_f32 v103, v103, s58, v174
	v_fma_f32 v104, v104, s58, v174
	v_fma_f32 v105, v105, s58, v174
	v_fma_f32 v106, v106, s58, v174
	v_fma_f32 v107, v107, s58, v174
	v_fma_f32 v108, v108, s58, v174
	v_fma_f32 v109, v109, s58, v174
	v_rsq_f32_e32 v94, v94
	v_rsq_f32_e32 v95, v95
	v_rsq_f32_e32 v96, v96
	v_rsq_f32_e32 v97, v97
	v_rsq_f32_e32 v98, v98
	v_rsq_f32_e32 v99, v99
	v_rsq_f32_e32 v100, v100
	v_rsq_f32_e32 v101, v101
	v_rsq_f32_e32 v102, v102
	v_rsq_f32_e32 v103, v103
	v_rsq_f32_e32 v104, v104
	v_rsq_f32_e32 v105, v105
	v_rsq_f32_e32 v106, v106
	v_rsq_f32_e32 v107, v107
	v_rsq_f32_e32 v108, v108
	v_rsq_f32_e32 v109, v109
	v_mul_f32_e32 v62, v94, v62
	v_mul_f32_e32 v63, v95, v63
	v_mul_f32_e32 v64, v96, v64
	v_mul_f32_e32 v65, v97, v65
	v_mul_f32_e32 v66, v98, v66
	v_mul_f32_e32 v67, v99, v67
	v_mul_f32_e32 v68, v100, v68
	v_mul_f32_e32 v69, v101, v69
	v_mul_f32_e32 v70, v102, v70
	v_mul_f32_e32 v71, v103, v71
	v_mul_f32_e32 v72, v104, v72
	v_mul_f32_e32 v73, v105, v73
	v_mul_f32_e32 v74, v106, v74
	v_mul_f32_e32 v75, v107, v75
	v_mul_f32_e32 v76, v108, v76
	v_mul_f32_e32 v77, v109, v77
	v_mul_f32_e32 v78, v94, v78
	v_mul_f32_e32 v79, v95, v79
	v_mul_f32_e32 v80, v96, v80
	v_mul_f32_e32 v81, v97, v81
	v_mul_f32_e32 v82, v98, v82
	v_mul_f32_e32 v83, v99, v83
	v_mul_f32_e32 v84, v100, v84
	v_mul_f32_e32 v85, v101, v85
	v_mul_f32_e32 v86, v102, v86
	v_mul_f32_e32 v87, v103, v87
	v_mul_f32_e32 v88, v104, v88
	v_mul_f32_e32 v89, v105, v89
	v_mul_f32_e32 v90, v106, v90
	v_mul_f32_e32 v91, v107, v91
	v_mul_f32_e32 v92, v108, v92
	v_mul_f32_e32 v93, v109, v93
	v_mul_f32_e32 v62, v11, v62
	v_mul_f32_e32 v63, v11, v63
; DI void phase_post(LAS unsigned char* lds, int l, bool do_qk) {
;     ...
;                     const float rs = rsqrtf(ss * (1.f / 64.f) + EPS); float y0 = x0 * rs * g0, y1 = x1 * rs * g1;
;                     const float p0 = __shfl_xor(y0, 8), p1 = __shfl_xor(y1, 8);
;                     if (!isctx) { y0 = y0 * c0 + sgn * p0 * s0; y1 = y1 * c1 + sgn * p1 * s1; }
	v_mul_f32_e32 v64, v11, v64
	v_mul_f32_e32 v65, v11, v65
	v_mul_f32_e32 v66, v11, v66
	v_mul_f32_e32 v67, v11, v67
	v_mul_f32_e32 v68, v11, v68
	v_mul_f32_e32 v69, v11, v69
	v_mul_f32_e32 v70, v13, v70
	v_mul_f32_e32 v71, v13, v71
	v_mul_f32_e32 v72, v13, v72
	v_mul_f32_e32 v73, v13, v73
	v_mul_f32_e32 v74, v13, v74
	v_mul_f32_e32 v75, v13, v75
	v_mul_f32_e32 v76, v13, v76
	v_mul_f32_e32 v77, v13, v77
	v_mul_f32_e32 v78, v12, v78
	v_mul_f32_e32 v79, v12, v79
	v_mul_f32_e32 v80, v12, v80
	v_mul_f32_e32 v81, v12, v81
	v_mul_f32_e32 v82, v12, v82
	v_mul_f32_e32 v83, v12, v83
	v_mul_f32_e32 v84, v12, v84
	v_mul_f32_e32 v85, v12, v85
	v_mul_f32_e32 v86, v14, v86
	v_mul_f32_e32 v87, v14, v87
	v_mul_f32_e32 v88, v14, v88
	v_mul_f32_e32 v89, v14, v89
	v_mul_f32_e32 v90, v14, v90
	v_mul_f32_e32 v91, v14, v91
	v_mul_f32_e32 v92, v14, v92
	v_mul_f32_e32 v93, v14, v93
	v_mov_b32_dpp v110, v62 row_ror:8 row_mask:0xf bank_mask:0xf
	v_mov_b32_dpp v111, v63 row_ror:8 row_mask:0xf bank_mask:0xf
	v_mov_b32_dpp v112, v64 row_ror:8 row_mask:0xf bank_mask:0xf
	v_mov_b32_dpp v113, v65 row_ror:8 row_mask:0xf bank_mask:0xf
	v_mov_b32_dpp v114, v66 row_ror:8 row_mask:0xf bank_mask:0xf
	v_mov_b32_dpp v115, v67 row_ror:8 row_mask:0xf bank_mask:0xf
	v_mov_b32_dpp v116, v68 row_ror:8 row_mask:0xf bank_mask:0xf
	v_mov_b32_dpp v117, v69 row_ror:8 row_mask:0xf bank_mask:0xf
	v_mov_b32_dpp v118, v70 row_ror:8 row_mask:0xf bank_mask:0xf
	v_mov_b32_dpp v119, v71 row_ror:8 row_mask:0xf bank_mask:0xf
	v_mov_b32_dpp v120, v72 row_ror:8 row_mask:0xf bank_mask:0xf
	v_mov_b32_dpp v121, v73 row_ror:8 row_mask:0xf bank_mask:0xf
	v_mov_b32_dpp v122, v74 row_ror:8 row_mask:0xf bank_mask:0xf
	v_mov_b32_dpp v123, v75 row_ror:8 row_mask:0xf bank_mask:0xf
	v_mov_b32_dpp v124, v76 row_ror:8 row_mask:0xf bank_mask:0xf
	v_mov_b32_dpp v125, v77 row_ror:8 row_mask:0xf bank_mask:0xf
	v_mov_b32_dpp v126, v78 row_ror:8 row_mask:0xf bank_mask:0xf
	v_mov_b32_dpp v127, v79 row_ror:8 row_mask:0xf bank_mask:0xf
	v_mov_b32_dpp v128, v80 row_ror:8 row_mask:0xf bank_mask:0xf
	v_mov_b32_dpp v129, v81 row_ror:8 row_mask:0xf bank_mask:0xf
	v_mov_b32_dpp v130, v82 row_ror:8 row_mask:0xf bank_mask:0xf
	v_mov_b32_dpp v131, v83 row_ror:8 row_mask:0xf bank_mask:0xf
	v_mov_b32_dpp v132, v84 row_ror:8 row_mask:0xf bank_mask:0xf
	v_mov_b32_dpp v133, v85 row_ror:8 row_mask:0xf bank_mask:0xf
	v_mov_b32_dpp v134, v86 row_ror:8 row_mask:0xf bank_mask:0xf
	v_mov_b32_dpp v135, v87 row_ror:8 row_mask:0xf bank_mask:0xf
	v_mov_b32_dpp v136, v88 row_ror:8 row_mask:0xf bank_mask:0xf
	v_mov_b32_dpp v137, v89 row_ror:8 row_mask:0xf bank_mask:0xf
	v_mov_b32_dpp v138, v90 row_ror:8 row_mask:0xf bank_mask:0xf
	v_mov_b32_dpp v139, v91 row_ror:8 row_mask:0xf bank_mask:0xf
	v_mov_b32_dpp v140, v92 row_ror:8 row_mask:0xf bank_mask:0xf
	v_mov_b32_dpp v141, v93 row_ror:8 row_mask:0xf bank_mask:0xf
	v_mul_f32_e32 v142, v25, v62
	v_mul_f32_e32 v143, v25, v63
	v_mul_f32_e32 v144, v25, v64
	v_mul_f32_e32 v145, v25, v65
	v_mul_f32_e32 v146, v25, v66
	v_mul_f32_e32 v147, v25, v67
	v_mul_f32_e32 v148, v25, v68
	v_mul_f32_e32 v149, v25, v69
	v_mul_f32_e32 v150, v25, v70
	v_mul_f32_e32 v151, v25, v71
	v_mul_f32_e32 v152, v25, v72
	v_mul_f32_e32 v153, v25, v73
	v_mul_f32_e32 v154, v25, v74
	v_mul_f32_e32 v155, v25, v75
	v_mul_f32_e32 v156, v25, v76
	v_mul_f32_e32 v157, v25, v77
	v_mul_f32_e32 v110, v15, v110
	v_mul_f32_e32 v111, v15, v111
	v_mul_f32_e32 v112, v15, v112
	v_mul_f32_e32 v113, v15, v113
	v_mul_f32_e32 v114, v15, v114
	v_mul_f32_e32 v115, v15, v115
	v_mul_f32_e32 v116, v15, v116
	v_mul_f32_e32 v117, v15, v117
	v_mul_f32_e32 v118, v15, v118
	v_mul_f32_e32 v119, v15, v119
	v_mul_f32_e32 v120, v15, v120
	v_mul_f32_e32 v121, v15, v121
	v_mul_f32_e32 v122, v15, v122
	v_mul_f32_e32 v123, v15, v123
	v_mul_f32_e32 v124, v15, v124
	v_mul_f32_e32 v125, v15, v125
	v_fmac_f32_e32 v142, v26, v110
	v_fmac_f32_e32 v143, v26, v111
	v_fmac_f32_e32 v144, v26, v112
	v_fmac_f32_e32 v145, v26, v113
	v_fmac_f32_e32 v146, v26, v114
	v_fmac_f32_e32 v147, v26, v115
	v_fmac_f32_e32 v148, v26, v116
	v_fmac_f32_e32 v149, v26, v117
	v_fmac_f32_e32 v150, v26, v118
	v_fmac_f32_e32 v151, v26, v119
	v_fmac_f32_e32 v152, v26, v120
	v_fmac_f32_e32 v153, v26, v121
	v_fmac_f32_e32 v154, v26, v122
	v_fmac_f32_e32 v155, v26, v123
	v_fmac_f32_e32 v156, v26, v124
	v_fmac_f32_e32 v157, v26, v125
	v_mul_f32_e32 v158, v24, v78
	v_mul_f32_e32 v159, v24, v79
	v_mul_f32_e32 v160, v24, v80
	v_mul_f32_e32 v161, v24, v81
	v_mul_f32_e32 v162, v24, v82
	v_mul_f32_e32 v163, v24, v83
	v_mul_f32_e32 v164, v24, v84
	v_mul_f32_e32 v165, v24, v85
	v_mul_f32_e32 v166, v24, v86
	v_mul_f32_e32 v167, v24, v87
	v_mul_f32_e32 v168, v24, v88
	v_mul_f32_e32 v169, v24, v89
	v_mul_f32_e32 v170, v24, v90
	v_mul_f32_e32 v171, v24, v91
	v_mul_f32_e32 v172, v24, v92
	v_mul_f32_e32 v173, v24, v93
	v_mul_f32_e32 v126, v15, v126
	v_mul_f32_e32 v127, v15, v127
	v_mul_f32_e32 v128, v15, v128
	v_mul_f32_e32 v129, v15, v129
	v_mul_f32_e32 v130, v15, v130
	v_mul_f32_e32 v131, v15, v131
	v_mul_f32_e32 v132, v15, v132
	v_mul_f32_e32 v133, v15, v133
	v_mul_f32_e32 v134, v15, v134
	v_mul_f32_e32 v135, v15, v135
	v_mul_f32_e32 v136, v15, v136
	v_mul_f32_e32 v137, v15, v137
	v_mul_f32_e32 v138, v15, v138
	v_mul_f32_e32 v139, v15, v139
	v_mul_f32_e32 v140, v15, v140
	v_mul_f32_e32 v141, v15, v141
	v_fmac_f32_e32 v158, v23, v126
	v_fmac_f32_e32 v159, v23, v127
	v_fmac_f32_e32 v160, v23, v128
	v_fmac_f32_e32 v161, v23, v129
	v_fmac_f32_e32 v162, v23, v130
	v_fmac_f32_e32 v163, v23, v131
	v_fmac_f32_e32 v164, v23, v132
	v_fmac_f32_e32 v165, v23, v133
	v_fmac_f32_e32 v166, v23, v134
	v_fmac_f32_e32 v167, v23, v135
; DI unsigned pk2(float lo, float hi) { return f2bf(lo) | (f2bf(hi) << 16); }
; DI void phase_post(LAS unsigned char* lds, int l, bool do_qk) {
;     ...
;                     if (!isctx) { y0 = y0 * c0 + sgn * p0 * s0; y1 = y1 * c1 + sgn * p1 * s1; }
;                     if (which == 0) { y0 *= QSCALE; y1 *= QSCALE; }
;                     wv[it] = pk2(y0, y1); }
; #pragma unroll
;                 for (int it = 0; it < 8; ++it) *(unsigned*)(base + it * 128 + lane * 2) = wv[it];
;             }
;         }
	v_fmac_f32_e32 v168, v23, v136
	v_fmac_f32_e32 v169, v23, v137
	v_fmac_f32_e32 v170, v23, v138
	v_fmac_f32_e32 v171, v23, v139
	v_fmac_f32_e32 v172, v23, v140
	v_fmac_f32_e32 v173, v23, v141
	v_cndmask_b32_e64 v62, v142, v62, s[6:7]
	v_cndmask_b32_e64 v63, v143, v63, s[6:7]
	v_cndmask_b32_e64 v64, v144, v64, s[6:7]
	v_cndmask_b32_e64 v65, v145, v65, s[6:7]
	v_cndmask_b32_e64 v66, v146, v66, s[6:7]
	v_cndmask_b32_e64 v67, v147, v67, s[6:7]
	v_cndmask_b32_e64 v68, v148, v68, s[6:7]
	v_cndmask_b32_e64 v69, v149, v69, s[6:7]
	v_cndmask_b32_e64 v70, v150, v70, s[6:7]
	v_cndmask_b32_e64 v71, v151, v71, s[6:7]
	v_cndmask_b32_e64 v72, v152, v72, s[6:7]
	v_cndmask_b32_e64 v73, v153, v73, s[6:7]
	v_cndmask_b32_e64 v74, v154, v74, s[6:7]
	v_cndmask_b32_e64 v75, v155, v75, s[6:7]
	v_cndmask_b32_e64 v76, v156, v76, s[6:7]
	v_cndmask_b32_e64 v77, v157, v77, s[6:7]
	v_cndmask_b32_e64 v78, v158, v78, s[6:7]
	v_cndmask_b32_e64 v79, v159, v79, s[6:7]
	v_cndmask_b32_e64 v80, v160, v80, s[6:7]
	v_cndmask_b32_e64 v81, v161, v81, s[6:7]
	v_cndmask_b32_e64 v82, v162, v82, s[6:7]
	v_cndmask_b32_e64 v83, v163, v83, s[6:7]
	v_cndmask_b32_e64 v84, v164, v84, s[6:7]
	v_cndmask_b32_e64 v85, v165, v85, s[6:7]
	v_cndmask_b32_e64 v86, v166, v86, s[6:7]
	v_cndmask_b32_e64 v87, v167, v87, s[6:7]
	v_cndmask_b32_e64 v88, v168, v88, s[6:7]
	v_cndmask_b32_e64 v89, v169, v89, s[6:7]
	v_cndmask_b32_e64 v90, v170, v90, s[6:7]
	v_cndmask_b32_e64 v91, v171, v91, s[6:7]
	v_cndmask_b32_e64 v92, v172, v92, s[6:7]
	v_cndmask_b32_e64 v93, v173, v93, s[6:7]
	v_mul_f32_e32 v62, 0x3e38aa3b, v62
	v_mul_f32_e32 v63, 0x3e38aa3b, v63
	v_mul_f32_e32 v64, 0x3e38aa3b, v64
	v_mul_f32_e32 v65, 0x3e38aa3b, v65
	v_mul_f32_e32 v66, 0x3e38aa3b, v66
	v_mul_f32_e32 v67, 0x3e38aa3b, v67
	v_mul_f32_e32 v68, 0x3e38aa3b, v68
	v_mul_f32_e32 v69, 0x3e38aa3b, v69
	v_mul_f32_e32 v78, 0x3e38aa3b, v78
	v_mul_f32_e32 v79, 0x3e38aa3b, v79
	v_mul_f32_e32 v80, 0x3e38aa3b, v80
	v_mul_f32_e32 v81, 0x3e38aa3b, v81
	v_mul_f32_e32 v82, 0x3e38aa3b, v82
	v_mul_f32_e32 v83, 0x3e38aa3b, v83
	v_mul_f32_e32 v84, 0x3e38aa3b, v84
	v_mul_f32_e32 v85, 0x3e38aa3b, v85
	v_bfe_u32 v142, v62, 16, 1
	v_bfe_u32 v143, v63, 16, 1
	v_bfe_u32 v144, v64, 16, 1
	v_bfe_u32 v145, v65, 16, 1
	v_bfe_u32 v146, v66, 16, 1
	v_bfe_u32 v147, v67, 16, 1
	v_bfe_u32 v148, v68, 16, 1
	v_bfe_u32 v149, v69, 16, 1
	v_bfe_u32 v150, v70, 16, 1
	v_bfe_u32 v151, v71, 16, 1
	v_bfe_u32 v152, v72, 16, 1
	v_bfe_u32 v153, v73, 16, 1
	v_bfe_u32 v154, v74, 16, 1
	v_bfe_u32 v155, v75, 16, 1
	v_bfe_u32 v156, v76, 16, 1
	v_bfe_u32 v157, v77, 16, 1
	v_bfe_u32 v158, v78, 16, 1
	v_bfe_u32 v159, v79, 16, 1
	v_bfe_u32 v160, v80, 16, 1
	v_bfe_u32 v161, v81, 16, 1
	v_bfe_u32 v162, v82, 16, 1
	v_bfe_u32 v163, v83, 16, 1
	v_bfe_u32 v164, v84, 16, 1
	v_bfe_u32 v165, v85, 16, 1
	v_bfe_u32 v166, v86, 16, 1
	v_bfe_u32 v167, v87, 16, 1
	v_bfe_u32 v168, v88, 16, 1
	v_bfe_u32 v169, v89, 16, 1
	v_bfe_u32 v170, v90, 16, 1
	v_bfe_u32 v171, v91, 16, 1
	v_bfe_u32 v172, v92, 16, 1
	v_bfe_u32 v173, v93, 16, 1
	v_add3_u32 v62, v62, v142, s59
	v_add3_u32 v63, v63, v143, s59
	v_add3_u32 v64, v64, v144, s59
	v_add3_u32 v65, v65, v145, s59
	v_add3_u32 v66, v66, v146, s59
	v_add3_u32 v67, v67, v147, s59
	v_add3_u32 v68, v68, v148, s59
	v_add3_u32 v69, v69, v149, s59
	v_add3_u32 v70, v70, v150, s59
	v_add3_u32 v71, v71, v151, s59
	v_add3_u32 v72, v72, v152, s59
	v_add3_u32 v73, v73, v153, s59
	v_add3_u32 v74, v74, v154, s59
	v_add3_u32 v75, v75, v155, s59
	v_add3_u32 v76, v76, v156, s59
	v_add3_u32 v77, v77, v157, s59
	v_add3_u32 v78, v78, v158, s59
	v_add3_u32 v79, v79, v159, s59
	v_add3_u32 v80, v80, v160, s59
	v_add3_u32 v81, v81, v161, s59
	v_add3_u32 v82, v82, v162, s59
	v_add3_u32 v83, v83, v163, s59
	v_add3_u32 v84, v84, v164, s59
	v_add3_u32 v85, v85, v165, s59
	v_add3_u32 v86, v86, v166, s59
	v_add3_u32 v87, v87, v167, s59
	v_add3_u32 v88, v88, v168, s59
	v_add3_u32 v89, v89, v169, s59
	v_add3_u32 v90, v90, v170, s59
	v_add3_u32 v91, v91, v171, s59
	v_add3_u32 v92, v92, v172, s59
	v_add3_u32 v93, v93, v173, s59
	v_lshrrev_b32_e32 v62, 16, v62
	v_lshrrev_b32_e32 v63, 16, v63
	v_lshrrev_b32_e32 v64, 16, v64
	v_lshrrev_b32_e32 v65, 16, v65
	v_lshrrev_b32_e32 v66, 16, v66
	v_lshrrev_b32_e32 v67, 16, v67
	v_lshrrev_b32_e32 v68, 16, v68
	v_lshrrev_b32_e32 v69, 16, v69
	v_lshrrev_b32_e32 v70, 16, v70
	v_lshrrev_b32_e32 v71, 16, v71
	v_lshrrev_b32_e32 v72, 16, v72
	v_lshrrev_b32_e32 v73, 16, v73
	v_lshrrev_b32_e32 v74, 16, v74
	v_lshrrev_b32_e32 v75, 16, v75
	v_lshrrev_b32_e32 v76, 16, v76
	v_lshrrev_b32_e32 v77, 16, v77
	v_and_or_b32 v46, v78, s9, v62
	v_and_or_b32 v47, v79, s9, v63
	v_and_or_b32 v48, v80, s9, v64
	v_and_or_b32 v49, v81, s9, v65
	v_and_or_b32 v50, v82, s9, v66
	v_and_or_b32 v51, v83, s9, v67
	v_and_or_b32 v52, v84, s9, v68
	v_and_or_b32 v53, v85, s9, v69
	v_and_or_b32 v54, v86, s9, v70
	v_and_or_b32 v55, v87, s9, v71
	v_and_or_b32 v56, v88, s9, v72
	v_and_or_b32 v57, v89, s9, v73
	v_and_or_b32 v58, v90, s9, v74
	v_and_or_b32 v59, v91, s9, v75
	v_and_or_b32 v60, v92, s9, v76
	v_and_or_b32 v61, v93, s9, v77
	global_store_dword v[6:7], v46, off
	global_store_dword v[6:7], v47, off offset:256
	global_store_dword v[6:7], v48, off offset:512
	global_store_dword v[6:7], v49, off offset:768
	global_store_dword v[6:7], v50, off offset:1024
	global_store_dword v[6:7], v51, off offset:1280
	global_store_dword v[6:7], v52, off offset:1536
	global_store_dword v[6:7], v53, off offset:1792
	global_store_dword v[8:9], v54, off
	global_store_dword v[8:9], v55, off offset:256
	global_store_dword v[8:9], v56, off offset:512
	global_store_dword v[8:9], v57, off offset:768
	global_store_dword v[8:9], v58, off offset:1024
	global_store_dword v[8:9], v59, off offset:1280
	global_store_dword v[8:9], v60, off offset:1536
	global_store_dword v[8:9], v61, off offset:1792
	s_mov_b64 s[20:21], 0
	v_add_u32_e32 v0, s25, v0
	s_movk_i32 s6, 0x41ff
	v_cmp_lt_i32_e32 vcc, s6, v0
	s_or_b64 s[18:19], vcc, s[18:19]
	s_andn2_b64 exec, exec, s[18:19]
	s_cbranch_execnz .LBB0_323
